# attention prologue: one strided load per lane touches the first item's Q block ahead of the K-tile loads
# baseline (speedup 1.0000x reference)
.LBB0_1117:
	s_cmp_le_i32 s79, s22
	s_cselect_b64 s[0:1], -1, 0
	s_and_b64 s[4:5], s[0:1], s[4:5]
	s_andn2_b64 vcc, exec, s[4:5]
	s_cbranch_vccnz .LBB0_1428
	s_mov_b64 s[8:9], s[92:93]
	v_writelane_b32 v254, s4, 41
	s_load_dwordx2 s[0:1], s[8:9], 0x70
	v_mbcnt_lo_u32_b32 v0, -1, 0
	v_mbcnt_hi_u32_b32 v0, -1, v0
	v_readlane_b32 s6, v253, 2
	v_writelane_b32 v254, s5, 42
	v_writelane_b32 v254, s26, 43
	v_add_u32_e32 v148, s37, v0
	s_movk_i32 s67, 0x81
	v_writelane_b32 v254, s27, 44
	v_writelane_b32 v254, s96, 45
	s_waitcnt lgkmcnt(0)
	v_writelane_b32 v254, s0, 46
	v_mov_b32_e32 v19, v148
	s_nop 0
	v_writelane_b32 v254, s1, 47
	v_writelane_b32 v254, s95, 48
	s_cmp_lg_u32 s95, 3
	s_cselect_b64 s[0:1], -1, 0
	v_writelane_b32 v254, s0, 49
	s_cmp_lt_i32 s95, 2
	s_nop 0
	v_writelane_b32 v254, s1, 50
	s_cselect_b64 s[0:1], -1, 0
	s_and_b64 s[4:5], s[0:1], exec
	s_cselect_b32 s53, 11, 10
	s_add_i32 s5, s53, -10
	s_lshl_b32 s5, s6, s5
	s_lshl_b32 s4, 1, s53
	s_mul_i32 s58, s5, s2
	s_lshr_b32 s4, s4, 1
	s_add_i32 s5, s58, s5
	s_min_i32 s59, s5, s4
	v_writelane_b32 v254, s95, 51
	s_cmp_ge_i32 s58, s59
	s_cbranch_scc1 .LBB0_1245
	v_readlane_b32 s28, v254, 51
	s_min_i32 s12, s28, 2
	s_load_dwordx2 s[6:7], s[8:9], 0x70
	s_lshl_b32 s40, s12, 1
	s_lshr_b32 s41, 0x4000, s40
	s_and_b64 s[4:5], s[0:1], exec
	s_brev_b32 s4, 64
	s_cselect_b32 s4, s4, 0x1000000
	s_waitcnt lgkmcnt(0)
	s_add_u32 s6, s6, 0x4000000
	s_addc_u32 s7, s7, 0
	s_lshl_b32 s13, s4, 1
	s_add_u32 s4, s6, s13
	s_addc_u32 s5, s7, 0
	s_sub_i32 s62, 6, s40
	s_and_b32 s11, s58, 63
	s_lshl_b32 s14, -1, s62
	s_andn2_b32 s18, s11, s14
	s_ashr_i32 s10, s58, 6
	s_lshr_b32 s15, s11, s62
	s_lshl_b32 s11, s18, 8
	s_add_i32 s19, s11, 0xffffff80
	s_ashr_i32 s11, s10, 31
	s_lshl_b64 s[10:11], s[10:11], 14
	s_mul_i32 s15, s15, s41
	s_ashr_i32 s20, s19, 31
	s_add_u32 s15, s19, s15
	s_addc_u32 s19, s20, 0
	v_ashrrev_i32_e32 v128, 4, v19
	s_add_u32 s10, s15, s10
	v_ashrrev_i32_e32 v129, 31, v128
	s_addc_u32 s11, s19, s11
	v_lshl_add_u64 v[0:1], s[10:11], 0, v[128:129]
	v_readlane_b32 s98, v253, 56
	v_mbcnt_lo_u32_b32 v178, -1, 0
	v_mbcnt_hi_u32_b32 v178, -1, v178
	s_add_i32 s98, s98, 0x80
	s_add_u32 s98, s10, s98
	s_addc_u32 s99, s11, 0
	s_lshl_b64 s[98:99], s[98:99], 8
	s_add_u32 s98, s6, s98
	s_addc_u32 s99, s7, s99
	v_lshlrev_b32_e32 v178, 7, v178
	v_and_b32_e32 v18, 15, v19
	v_lshlrev_b64 v[0:1], 8, v[0:1]
	v_lshl_add_u64 v[0:1], s[4:5], 0, v[0:1]
	v_lshlrev_b32_e32 v138, 4, v18
	s_cmp_lg_u32 s18, 0
	s_cselect_b64 s[10:11], -1, 0
	s_cmp_eq_u32 s18, 0
	v_lshl_add_u64 v[16:17], v[0:1], 0, v[138:139]
	s_waitcnt vmcnt(0)
	s_barrier
	global_load_dword v179, v178, s[98:99]
	s_cbranch_scc1 .LBB0_1121
	global_load_dwordx4 v[0:3], v[16:17], off
	s_branch .LBB0_1122
